# v69 plus phase-start code prefetch: in front of every late barrier wait, at the top of P5 and of P9, every thread reads a 128-byte slice of the code its workgroup is about to run (windows sized from t
# baseline (speedup 1.0000x reference)
.Lh1b_main:
	v_ashrrev_i32_e32 v2, 31, v10
	v_lshrrev_b32_e32 v2, 26, v2
	v_add_u32_e32 v2, v10, v2
	v_ashrrev_i32_e32 v11, 6, v2
	v_bfe_i32 v2, v10, 27, 1
	v_lshlrev_b32_e32 v1, 4, v10
	v_lshrrev_b32_e32 v2, 22, v2
	v_add_u32_e32 v2, v1, v2
	v_and_b32_e32 v2, 0xfffffc00, v2
	v_sub_u32_e32 v2, v1, v2
	v_lshrrev_b32_e32 v3, 4, v2
	v_bitop3_b32 v2, v3, v2, 32 bitop3:0x6c
	v_ashrrev_i32_e32 v4, 31, v2
	v_lshrrev_b32_e32 v4, 26, v4
	v_add_u32_e32 v4, v2, v4
	v_lshlrev_b32_e32 v3, 3, v11
	v_ashrrev_i32_e32 v12, 6, v4
	v_and_b32_e32 v4, 0xc0, v4
	v_and_b32_e32 v3, -16, v3
	v_sub_u32_e32 v2, v2, v4
	v_mov_b32_e32 v4, 1
	v_add_u32_e32 v3, v12, v3
	v_ashrrev_i16_sdwa v2, v4, sext(v2) dst_sel:DWORD dst_unused:UNUSED_PAD src0_sel:DWORD src1_sel:BYTE_0
	v_lshlrev_b32_e32 v5, 5, v11
	v_bfe_i32 v13, v2, 0, 16
	v_lshlrev_b32_e32 v2, 1, v3
	v_lshrrev_b32_e32 v6, 2, v3
	v_and_b32_e32 v7, 3, v12
	s_mov_b32 s3, 0x1fffe0
	v_and_b32_e32 v5, 32, v5
	v_and_b32_e32 v2, 24, v2
	v_and_b32_e32 v6, 4, v6
	v_and_or_b32 v7, v3, s3, v7
	v_or3_b32 v2, v7, v6, v2
	v_add_lshl_u32 v5, v5, v13, 1
	v_add_u32_e32 v1, 0x2000, v1
	v_lshl_add_u32 v132, v2, 11, v5
	v_ashrrev_i32_e32 v2, 31, v1
	v_lshrrev_b32_e32 v2, 22, v2
	v_add_u32_e32 v2, v1, v2
	v_ashrrev_i32_e32 v14, 10, v2
	v_mul_i32_i24_e32 v2, 0x400, v14
	v_sub_u32_e32 v1, v1, v2
	v_lshrrev_b32_e32 v2, 4, v1
	v_bitop3_b32 v1, v2, v1, 32 bitop3:0x6c
	v_lshl_add_u32 v130, v3, 11, v5
	v_ashrrev_i32_e32 v3, 31, v1
	v_lshrrev_b32_e32 v3, 26, v3
	v_add_u32_e32 v3, v1, v3
	v_lshlrev_b32_e32 v2, 3, v14
	v_ashrrev_i32_e32 v15, 6, v3
	v_and_b32_e32 v3, 0xc0, v3
	v_and_b32_e32 v2, -16, v2
	v_sub_u32_e32 v1, v1, v3
	v_add_u32_e32 v2, v15, v2
	v_ashrrev_i16_sdwa v1, v4, sext(v1) dst_sel:DWORD dst_unused:UNUSED_PAD src0_sel:DWORD src1_sel:BYTE_0
	v_and_b32_e32 v4, 3, v15
	s_ashr_i32 s4, s0, 6
	s_ashr_i32 s71, s70, 31
	s_ashr_i32 s9, s8, 31
	s_ashr_i32 s1, s0, 8
	v_and_or_b32 v4, v2, s3, v4
	s_lshl_b32 s3, s4, 10
	s_lshl_b64 s[6:7], s[70:71], 19
	s_lshl_b64 s[10:11], s[8:9], 19
	s_add_u32 s74, s18, s10
	v_lshlrev_b32_e32 v5, 5, v14
	v_bfe_i32 v16, v1, 0, 16
	v_lshlrev_b32_e32 v1, 1, v2
	v_lshrrev_b32_e32 v3, 2, v2
	s_addc_u32 s75, s19, s11
	s_add_i32 s13, s3, 0
	v_and_b32_e32 v5, 32, v5
	v_and_b32_e32 v1, 24, v1
	v_and_b32_e32 v3, 4, v3
	s_add_i32 m0, s13, 0x10000
	v_or3_b32 v1, v4, v3, v1
	v_add_lshl_u32 v3, v5, v16, 1
	s_getpc_b64 s[100:101]
	v_lshlrev_b32_e32 v243, 7, v0
	v_min_u32_e32 v243, 0x1f80, v243
	global_load_dword v243, v243, s[100:101]
	v_readfirstlane_b32 s98, v0
	s_cmp_gt_u32 s98, 63
	s_cbranch_scc1 .Lh1a_done
	s_getreg_b32 s98, hwreg(HW_REG_XCC_ID, 0, 4)
	s_lshl_b32 s98, s98, 8
	v_mov_b32_e32 v230, s98
	v_add_u32_e32 v230, 0x6400, v230
	s_mov_b32 s98, 0

.LBB0_272:
	s_or_b64 exec, exec, s[6:7]
	s_add_u32 s92, s54, 0xa000000
	s_addc_u32 s93, s55, 0
	s_add_u32 s82, s54, 0x2400
	s_addc_u32 s83, s55, 0
	s_add_u32 s80, s54, 0xd000000
	v_mov_b32_e32 v130, v0
	s_addc_u32 s81, s55, 0
	s_waitcnt lgkmcnt(0)
	s_mov_b64 s[4:5], -1
	s_andn2_b64 vcc, exec, s[16:17]
	v_bfe_u32 v88, v130, 4, 2
	v_and_b32_e32 v135, 15, v130
	v_lshlrev_b32_e32 v89, 4, v130
	v_ashrrev_i32_e32 v1, 4, v130
	v_lshlrev_b32_e32 v141, 2, v130
	v_cmp_eq_u32_e64 s[34:35], 0, v130
	s_cbranch_vccnz .LBB0_279
	v_add_u32_e32 v4, 0x200, v130
	v_and_b32_e32 v66, 0xf0, v89
	v_ashrrev_i32_e32 v90, 4, v4
	v_add_u32_e32 v4, 0x400, v130
	s_add_i32 s0, 0, 0x11000
	v_and_b32_e32 v7, 12, v141
	v_ashrrev_i32_e32 v91, 4, v4
	v_add_u32_e32 v4, 0x600, v130
	v_add_u32_e32 v5, s0, v66
	v_lshlrev_b32_e32 v93, 1, v7
	v_sub_u32_e32 v7, 0xff, v1
	s_movk_i32 s0, 0x110
	v_ashrrev_i32_e32 v92, 4, v4
	v_add_u32_e32 v4, 0, v66
	v_cvt_f32_i32_e32 v94, v7
	v_mul_lo_u32 v7, v1, s0
	v_add_u32_e32 v96, v4, v7
	v_add_u32_e32 v97, v5, v7
	v_sub_u32_e32 v7, 0xff, v90
	v_cvt_f32_i32_e32 v98, v7
	v_mul_lo_u32 v7, v90, s0
	v_add_u32_e32 v100, v4, v7
	v_add_u32_e32 v101, v5, v7
	v_sub_u32_e32 v7, 0xff, v91
	v_cvt_f32_i32_e32 v102, v7
	v_mul_lo_u32 v7, v91, s0
	v_add_u32_e32 v104, v4, v7
	v_add_u32_e32 v105, v5, v7
	v_sub_u32_e32 v7, 0xff, v92
	v_cvt_f32_i32_e32 v106, v7
	v_mul_lo_u32 v7, v92, s0
	v_add_u32_e32 v108, v4, v7
	v_add_u32_e32 v109, v5, v7
	v_add_u32_e32 v4, 0x80, v1
	v_sub_u32_e32 v5, 0x7f, v1
	v_cvt_f32_i32_e32 v112, v5
	v_cvt_f32_i32_e32 v113, v4
	v_add_u32_e32 v4, 0x80, v90
	v_sub_u32_e32 v5, 0x7f, v90
	s_lshl_b32 s3, s38, 1
	v_cvt_f32_i32_e32 v114, v5
	v_cvt_f32_i32_e32 v115, v4
	v_add_u32_e32 v4, 0x80, v91
	v_sub_u32_e32 v5, 0x7f, v91
	s_add_i32 s36, s3, 0xfffffec0
	v_cvt_f32_i32_e32 v116, v5
	v_cvt_f32_i32_e32 v117, v4
	v_add_u32_e32 v4, 0x80, v92
	v_sub_u32_e32 v5, 0x7f, v92
	s_bfe_u32 s18, s38, 0x20002
	v_readlane_b32 s0, v242, 0
	v_bfe_u32 v6, v130, 2, 2
	v_cvt_f32_i32_e32 v95, v1
	v_cvt_f32_i32_e32 v99, v90
	v_cvt_f32_i32_e32 v103, v91
	v_cvt_f32_i32_e32 v107, v92
	v_cvt_f32_i32_e32 v118, v5
	v_cvt_f32_i32_e32 v119, v4
	s_lshl_b32 s16, s18, 2
	v_readlane_b32 s4, v242, 4
	v_mov_b32_e32 v67, 0
	v_lshl_or_b32 v6, v88, 3, v6
	v_lshlrev_b32_e32 v4, 7, v135
	v_readlane_b32 s5, v242, 5
	s_add_u32 s16, s4, s16
	s_mov_b32 s73, 0
	v_lshl_add_u64 v[2:3], s[68:69], 0, v[66:67]
	v_mul_u32_u24_e32 v110, 0x110, v6
	v_lshlrev_b32_e32 v6, 2, v88
	v_or_b32_e32 v8, 0x800, v4
	v_or_b32_e32 v10, 0x1000, v4
	v_or_b32_e32 v12, 0x1800, v4
	v_or_b32_e32 v14, 0x2000, v4
	v_or_b32_e32 v16, 0x2800, v4
	v_or_b32_e32 v18, 0x3000, v4
	v_or_b32_e32 v20, 0x3800, v4
	v_readlane_b32 s1, v242, 1
	v_readlane_b32 s10, v242, 10
	v_readlane_b32 s11, v242, 11
	s_addc_u32 s17, s5, 0
	s_lshl_b32 s72, s18, 8
	v_add3_u32 v111, 0, v93, v110
	v_lshl_add_u64 v[68:69], v[2:3], 0, s[72:73]
	s_mov_b64 s[18:19], -1
	s_mov_b32 s0, 0xbfb8aa3b
	s_mov_b32 s1, 0x42ce8ed0
	s_mov_b32 s10, 0xc2b17218
	s_mov_b32 s11, 0x7f800000
	s_mov_b32 s24, 0x3f2aaaab
	v_mov_b32_e32 v120, 0x3ecc95a3
	s_mov_b32 s25, 0x3f317218
	s_mov_b32 s26, 0x33800000
	s_movk_i32 s27, 0x1400
	s_mov_b32 s28, 0x8800
	v_lshlrev_b32_e32 v70, 1, v6
	v_lshlrev_b32_e32 v72, 1, v4
	v_lshlrev_b32_e32 v74, 1, v8
	v_lshlrev_b32_e32 v76, 1, v10
	v_lshlrev_b32_e32 v66, 1, v12
	v_lshlrev_b32_e32 v78, 1, v14
	v_lshlrev_b32_e32 v80, 1, v16
	v_lshlrev_b32_e32 v82, 1, v18
	v_lshlrev_b32_e32 v84, 1, v20
	v_mov_b32_e32 v121, 0x7f800000
	v_mov_b32_e32 v86, 0x3f317218
	v_mov_b32_e32 v71, v67
	v_mov_b32_e32 v73, v67
	v_mov_b32_e32 v75, v67
	v_mov_b32_e32 v77, v67
	s_mov_b32 s5, 0
	v_readlane_b32 s2, v242, 2
	v_readlane_b32 s3, v242, 3
	v_readlane_b32 s6, v242, 6
	v_readlane_b32 s7, v242, 7
	v_readlane_b32 s8, v242, 8
	v_readlane_b32 s9, v242, 9
	v_readlane_b32 s12, v242, 12
	v_readlane_b32 s13, v242, 13
	v_readlane_b32 s14, v242, 14
	v_readlane_b32 s15, v242, 15
	s_getpc_b64 s[100:101]
	v_lshlrev_b32_e32 v243, 7, v0
	v_min_u32_e32 v243, 0x6800, v243
	global_load_dword v243, v243, s[100:101]
	v_readfirstlane_b32 s98, v0
	s_cmp_gt_u32 s98, 63
	s_cbranch_scc1 .Lh2a_done
	s_getreg_b32 s98, hwreg(HW_REG_XCC_ID, 0, 4)
	s_lshl_b32 s98, s98, 8
	v_mov_b32_e32 v232, s98
	v_add_u32_e32 v232, 0x6400, v232
	s_mov_b32 s98, 0

.LBB0_279:
	s_and_b64 vcc, exec, s[4:5]
	s_cbranch_vccz .LBB0_291
	s_getpc_b64 s[100:101]
	v_lshlrev_b32_e32 v243, 7, v0
	v_min_u32_e32 v243, 0x4980, v243
	global_load_dword v243, v243, s[100:101]
	v_readfirstlane_b32 s98, v0
	s_cmp_gt_u32 s98, 63
	s_cbranch_scc1 .Lh2b_done
	s_getreg_b32 s98, hwreg(HW_REG_XCC_ID, 0, 4)
	s_lshl_b32 s98, s98, 8
	v_mov_b32_e32 v232, s98
	v_add_u32_e32 v232, 0x6400, v232
	s_mov_b32 s98, 0

.LBB0_360:
	s_or_b64 exec, exec, s[6:7]
	s_getpc_b64 s[100:101]
	v_lshlrev_b32_e32 v243, 7, v0
	v_min_u32_e32 v243, 0xbf80, v243
	global_load_dword v243, v243, s[100:101]
	s_add_u32 s60, s54, 0xb800000
	s_addc_u32 s61, s55, 0
	s_cmpk_gt_i32 s38, 0x7f
	s_waitcnt lgkmcnt(0)
	s_barrier
	s_cbranch_scc0 .LBB0_365
	s_cmpk_lt_u32 s38, 0x80
	s_mov_b64 s[14:15], 0
	s_cbranch_scc0 .LBB0_366
	s_and_b32 s0, s38, 3
	s_lshl_b32 s1, s0, 2
	v_readlane_b32 s16, v242, 0
	v_mov_b32_e32 v4, v0
	v_mov_b32_e32 v1, s1
	v_readlane_b32 s20, v242, 4
	v_readlane_b32 s21, v242, 5
	s_nop 4
	global_load_dword v2, v1, s[20:21]
	global_load_dword v5, v1, s[20:21] offset:16
	s_mov_b32 s7, 0xbfb8aa3b
	s_mov_b32 s8, 0x42ce8ed0
	s_mov_b32 s9, 0xc2b17218
	v_mov_b32_e32 v8, 0x7f800000
	s_mov_b32 s10, 0x3f2aaaab
	s_mov_b32 s6, 0x3f317218
	v_mov_b32_e32 v9, 0x3ecc95a3
	s_mov_b32 s4, 0x7f800000
	s_mov_b32 s5, 0x33800000
	v_mov_b32_e32 v10, 0x3f2aaada
	s_lshl_b32 s1, s38, 6
	s_add_i32 s1, s1, 0x7fffe000
	v_readfirstlane_b32 s11, v4
	s_and_b32 s3, s1, 0x7fffff00
	s_ashr_i32 s1, s11, 6
	v_and_b32_e32 v12, 15, v4
	s_lshl_b32 s16, s0, 8
	v_readlane_b32 s18, v242, 2
	v_mov_b32_e32 v3, 0
	s_movk_i32 s18, 0x1400
	v_readlane_b32 s17, v242, 1
	s_mov_b32 s17, 0
	v_bfe_u32 v13, v4, 4, 2
	v_and_b32_e32 v1, 63, v4
	v_readlane_b32 s19, v242, 3
	v_readlane_b32 s22, v242, 6
	v_readlane_b32 s23, v242, 7
	v_readlane_b32 s24, v242, 8
	v_readlane_b32 s25, v242, 9
	v_readlane_b32 s26, v242, 10
	s_movk_i32 s19, 0xffee
	s_movk_i32 s20, 0xffed
	s_movk_i32 s21, 0xffdf
	s_movk_i32 s22, 0xffde
	s_movk_i32 s23, 0xffdd
	s_movk_i32 s24, 0xffcf
	s_movk_i32 s25, 0xffce
	s_movk_i32 s26, 0xffcd
	v_mov_b32_e32 v34, v3
	v_mov_b32_e32 v35, v3
	v_mov_b32_e32 v36, v3
	v_mov_b32_e32 v37, v3
	v_mov_b32_e32 v38, v3
	v_mov_b32_e32 v39, v3
	v_mov_b32_e32 v40, v3
	v_mov_b32_e32 v41, v3
	v_mov_b32_e32 v50, v3
	v_mov_b32_e32 v51, v3
	v_mov_b32_e32 v52, v3
	v_mov_b32_e32 v53, v3
	v_mov_b32_e32 v66, v3
	v_mov_b32_e32 v67, v3
	v_mov_b32_e32 v68, v3
	v_mov_b32_e32 v69, v3
	v_mov_b32_e32 v25, v3
	v_mov_b32_e32 v26, v3
	v_mov_b32_e32 v27, v3
	v_mov_b32_e32 v28, v3
	v_mov_b32_e32 v29, v3
	v_mov_b32_e32 v30, v3
	v_mov_b32_e32 v31, v3
	v_mov_b32_e32 v32, v3
	v_mov_b32_e32 v33, v3
	v_mov_b32_e32 v62, v3
	v_mov_b32_e32 v63, v3
	v_mov_b32_e32 v64, v3
	v_mov_b32_e32 v65, v3
	v_mov_b32_e32 v70, v3
	v_mov_b32_e32 v71, v3
	v_mov_b32_e32 v72, v3
	v_mov_b32_e32 v73, v3
	v_mov_b32_e32 v74, v3
	v_mov_b32_e32 v75, v3
	v_mov_b32_e32 v76, v3
	v_mov_b32_e32 v77, v3
	v_mov_b32_e32 v94, v3
	v_mov_b32_e32 v95, v3
	v_mov_b32_e32 v96, v3
	s_waitcnt vmcnt(1)
	v_mul_f32_e32 v6, 0xbfb8aa3b, v2
	v_fma_f32 v11, v2, s7, -v6
	v_rndne_f32_e32 v14, v6
	v_fmac_f32_e32 v11, 0xb2a5705f, v2
	v_sub_f32_e32 v6, v6, v14
	v_add_f32_e32 v6, v6, v11
	v_cvt_i32_f32_e32 v14, v14
	v_exp_f32_e32 v6, v6
	s_waitcnt vmcnt(0)
	v_mul_f32_e32 v7, 0xbfb8aa3b, v5
	v_cmp_nlt_f32_e32 vcc, s8, v2
	v_fma_f32 v15, v5, s7, -v7
	v_ldexp_f32 v6, v6, v14
	v_rndne_f32_e32 v16, v7
	v_cndmask_b32_e32 v6, 0, v6, vcc
	v_cmp_ngt_f32_e32 vcc, s9, v2
	v_fmac_f32_e32 v15, 0xb2a5705f, v5
	v_sub_f32_e32 v7, v7, v16
	v_cndmask_b32_e32 v2, v8, v6, vcc
	v_add_f32_e32 v7, v7, v15
	v_add_f32_e32 v14, 1.0, v2
	v_cvt_i32_f32_e32 v11, v16
	v_exp_f32_e32 v15, v7
	v_add_f32_e32 v16, -1.0, v14
	v_frexp_mant_f32_e32 v17, v14
	v_cvt_f64_f32_e32 v[6:7], v14
	v_sub_f32_e32 v18, v16, v14
	v_frexp_exp_i32_f64_e32 v6, v[6:7]
	v_cmp_gt_f32_e32 vcc, s10, v17
	v_sub_f32_e32 v16, v2, v16
	v_add_f32_e32 v7, 1.0, v18
	v_subbrev_co_u32_e32 v6, vcc, 0, v6, vcc
	v_add_f32_e32 v7, v16, v7
	v_sub_u32_e32 v16, 0, v6
	v_cvt_f32_i32_e32 v6, v6
	v_ldexp_f32 v14, v14, v16
	v_ldexp_f32 v7, v7, v16
	v_add_f32_e32 v16, -1.0, v14
	v_add_f32_e32 v17, 1.0, v14
	v_add_f32_e32 v18, 1.0, v16
	v_add_f32_e32 v19, -1.0, v17
	v_sub_f32_e32 v18, v14, v18
	v_sub_f32_e32 v14, v14, v19
	v_mul_f32_e32 v19, 0x3f317218, v6
	v_add_f32_e32 v18, v7, v18
	v_add_f32_e32 v7, v7, v14
	v_fma_f32 v14, v6, s6, -v19
	v_add_f32_e32 v20, v16, v18
	v_add_f32_e32 v21, v17, v7
	v_fmac_f32_e32 v14, 0xb102e308, v6
	v_sub_f32_e32 v6, v16, v20
	v_sub_f32_e32 v16, v17, v21
	v_rcp_f32_e32 v17, v21
	v_add_f32_e32 v22, v19, v14
	v_add_f32_e32 v7, v7, v16
	v_sub_f32_e32 v16, v22, v19
	v_sub_f32_e32 v14, v14, v16
	v_mul_f32_e32 v16, v20, v17
	v_add_f32_e32 v6, v18, v6
	v_mul_f32_e32 v18, v21, v16
	v_fma_f32 v19, v16, v21, -v18
	v_fmac_f32_e32 v19, v16, v7
	v_add_f32_e32 v23, v18, v19
	v_sub_f32_e32 v24, v20, v23
	v_sub_f32_e32 v18, v23, v18
	v_sub_f32_e32 v20, v20, v24
	v_sub_f32_e32 v18, v18, v19
	v_sub_f32_e32 v19, v20, v23
	v_add_f32_e32 v6, v6, v19
	v_add_f32_e32 v6, v18, v6
	v_add_f32_e32 v18, v24, v6
	v_mul_f32_e32 v19, v17, v18
	v_sub_f32_e32 v20, v24, v18
	v_mul_f32_e32 v23, v21, v19
	v_add_f32_e32 v6, v6, v20
	v_add_f32_e32 v20, v16, v19
	v_fma_f32 v21, v19, v21, -v23
	v_sub_f32_e32 v16, v20, v16
	v_fmac_f32_e32 v21, v19, v7
	v_sub_f32_e32 v7, v19, v16
	v_add_f32_e32 v16, v23, v21
	v_sub_f32_e32 v19, v16, v23
	v_sub_f32_e32 v23, v18, v16
	v_sub_f32_e32 v18, v18, v23
	v_sub_f32_e32 v16, v18, v16
	v_sub_f32_e32 v19, v19, v21
	v_add_f32_e32 v6, v6, v16
	v_add_f32_e32 v6, v19, v6
	v_add_f32_e32 v6, v23, v6
	v_mul_f32_e32 v6, v17, v6
	v_add_f32_e32 v6, v7, v6
	v_add_f32_e32 v7, v20, v6
	v_mul_f32_e32 v16, v7, v7
	v_fmamk_f32 v19, v16, 0x3e9b6dac, v9
	v_sub_f32_e32 v17, v7, v20
	v_ldexp_f32 v18, v7, 1
	v_mul_f32_e32 v7, v7, v16
	v_fmaak_f32 v16, v16, v19, 0x3f2aaada
	v_mul_f32_e32 v7, v7, v16
	v_add_f32_e32 v16, v18, v7
	v_sub_f32_e32 v6, v6, v17
	v_sub_f32_e32 v17, v16, v18
	v_ldexp_f32 v6, v6, 1
	v_sub_f32_e32 v7, v7, v17
	v_add_f32_e32 v6, v6, v7
	v_add_f32_e32 v7, v16, v6
	v_sub_f32_e32 v16, v7, v16
	v_add_f32_e32 v17, v22, v7
	v_sub_f32_e32 v6, v6, v16
	v_sub_f32_e32 v16, v17, v22
	v_sub_f32_e32 v18, v17, v16
	v_sub_f32_e32 v7, v7, v16
	v_add_f32_e32 v16, v14, v6
	v_sub_f32_e32 v18, v22, v18
	v_sub_f32_e32 v19, v16, v14
	v_add_f32_e32 v7, v7, v18
	v_sub_f32_e32 v18, v16, v19
	v_sub_f32_e32 v6, v6, v19
	v_sub_f32_e32 v14, v14, v18
	v_add_f32_e32 v7, v16, v7
	v_add_f32_e32 v6, v6, v14
	v_add_f32_e32 v14, v17, v7
	v_sub_f32_e32 v16, v14, v17
	v_sub_f32_e32 v7, v7, v16
	v_add_f32_e32 v6, v6, v7
	v_add_f32_e32 v6, v14, v6
	v_cmp_neq_f32_e32 vcc, s4, v2
	v_mov_b32_e32 v21, v3
	v_mov_b32_e32 v22, v3
	v_cndmask_b32_e32 v6, v8, v6, vcc
	v_cmp_lt_f32_e64 vcc, |v2|, s5
	v_mov_b32_e32 v23, v3
	v_mov_b32_e32 v24, v3
	v_cndmask_b32_e32 v2, v6, v2, vcc
	v_mul_f32_e32 v140, 0xbfb8aa3b, v2
	v_ldexp_f32 v2, v15, v11
	v_cmp_nlt_f32_e32 vcc, s8, v5
	s_mul_i32 s8, s1, 0x1200
	v_exp_f32_e64 v145, -v140
	v_cndmask_b32_e32 v2, 0, v2, vcc
	v_cmp_ngt_f32_e32 vcc, s9, v5
	v_mov_b32_e32 v97, v3
	v_readlane_b32 s27, v242, 11
	v_cndmask_b32_e32 v2, v8, v2, vcc
	v_add_f32_e32 v5, 1.0, v2
	v_add_f32_e32 v6, -1.0, v5
	v_sub_f32_e32 v7, v6, v5
	v_add_f32_e32 v7, 1.0, v7
	v_sub_f32_e32 v6, v2, v6
	v_add_f32_e32 v11, v6, v7
	v_frexp_mant_f32_e32 v14, v5
	v_cvt_f64_f32_e32 v[6:7], v5
	v_frexp_exp_i32_f64_e32 v6, v[6:7]
	v_cmp_gt_f32_e32 vcc, s10, v14
	v_readlane_b32 s28, v242, 12
	v_readlane_b32 s29, v242, 13
	v_subbrev_co_u32_e32 v6, vcc, 0, v6, vcc
	v_sub_u32_e32 v7, 0, v6
	v_ldexp_f32 v5, v5, v7
	v_ldexp_f32 v7, v11, v7
	v_add_f32_e32 v11, -1.0, v5
	v_add_f32_e32 v16, 1.0, v5
	v_add_f32_e32 v14, 1.0, v11
	v_add_f32_e32 v17, -1.0, v16
	v_sub_f32_e32 v14, v5, v14
	v_sub_f32_e32 v5, v5, v17
	v_add_f32_e32 v5, v7, v5
	v_add_f32_e32 v14, v7, v14
	v_add_f32_e32 v7, v16, v5
	v_rcp_f32_e32 v17, v7
	v_add_f32_e32 v15, v11, v14
	v_sub_f32_e32 v11, v11, v15
	v_add_f32_e32 v11, v14, v11
	v_sub_f32_e32 v14, v16, v7
	v_add_f32_e32 v5, v5, v14
	v_mul_f32_e32 v14, v15, v17
	v_mul_f32_e32 v16, v7, v14
	v_fma_f32 v18, v14, v7, -v16
	v_fmac_f32_e32 v18, v14, v5
	v_add_f32_e32 v19, v16, v18
	v_sub_f32_e32 v20, v15, v19
	v_sub_f32_e32 v15, v15, v20
	v_sub_f32_e32 v16, v19, v16
	v_sub_f32_e32 v15, v15, v19
	v_add_f32_e32 v11, v11, v15
	v_sub_f32_e32 v15, v16, v18
	v_add_f32_e32 v11, v15, v11
	v_add_f32_e32 v15, v20, v11
	v_mul_f32_e32 v16, v17, v15
	v_mul_f32_e32 v18, v7, v16
	v_fma_f32 v7, v16, v7, -v18
	v_fmac_f32_e32 v7, v16, v5
	v_sub_f32_e32 v5, v20, v15
	v_add_f32_e32 v5, v11, v5
	v_add_f32_e32 v11, v18, v7
	v_sub_f32_e32 v19, v15, v11
	v_sub_f32_e32 v15, v15, v19
	v_sub_f32_e32 v18, v11, v18
	v_sub_f32_e32 v11, v15, v11
	v_add_f32_e32 v5, v5, v11
	v_sub_f32_e32 v7, v18, v7
	v_add_f32_e32 v5, v7, v5
	v_add_f32_e32 v7, v14, v16
	v_add_f32_e32 v5, v19, v5
	v_sub_f32_e32 v11, v7, v14
	v_mul_f32_e32 v5, v17, v5
	v_sub_f32_e32 v11, v16, v11
	v_add_f32_e32 v5, v11, v5
	v_cvt_f32_i32_e32 v6, v6
	v_add_f32_e32 v11, v7, v5
	v_mul_f32_e32 v14, v11, v11
	v_fmac_f32_e32 v9, 0x3e9b6dac, v14
	v_fmac_f32_e32 v10, v14, v9
	v_mul_f32_e32 v9, 0x3f317218, v6
	v_fma_f32 v15, v6, s6, -v9
	v_fmac_f32_e32 v15, 0xb102e308, v6
	v_sub_f32_e32 v6, v11, v7
	v_sub_f32_e32 v5, v5, v6
	v_add_f32_e32 v6, v9, v15
	v_sub_f32_e32 v7, v6, v9
	v_ldexp_f32 v9, v11, 1
	v_mul_f32_e32 v11, v11, v14
	v_mul_f32_e32 v10, v11, v10
	v_add_f32_e32 v11, v9, v10
	v_sub_f32_e32 v9, v11, v9
	v_ldexp_f32 v5, v5, 1
	v_sub_f32_e32 v9, v10, v9
	v_add_f32_e32 v5, v5, v9
	v_add_f32_e32 v9, v11, v5
	v_sub_f32_e32 v10, v9, v11
	v_sub_f32_e32 v5, v5, v10
	v_add_f32_e32 v10, v6, v9
	v_sub_f32_e32 v11, v10, v6
	v_sub_f32_e32 v14, v10, v11
	v_sub_f32_e32 v7, v15, v7
	v_sub_f32_e32 v6, v6, v14
	v_sub_f32_e32 v9, v9, v11
	v_add_f32_e32 v6, v9, v6
	v_add_f32_e32 v9, v7, v5
	v_sub_f32_e32 v11, v9, v7
	v_sub_f32_e32 v14, v9, v11
	v_sub_f32_e32 v7, v7, v14
	v_sub_f32_e32 v5, v5, v11
	v_add_f32_e32 v6, v9, v6
	v_add_f32_e32 v5, v5, v7
	v_add_f32_e32 v7, v10, v6
	v_sub_f32_e32 v9, v7, v10
	v_sub_f32_e32 v6, v6, v9
	v_add_f32_e32 v5, v5, v6
	v_add_f32_e32 v5, v7, v5
	v_cmp_neq_f32_e32 vcc, s4, v2
	s_lshl_b32 s4, s0, 7
	v_ashrrev_i32_e32 v15, 4, v4
	v_cndmask_b32_e32 v5, v8, v5, vcc
	v_cmp_lt_f32_e64 vcc, |v2|, s5
	s_lshl_b32 s5, s1, 5
	s_add_u32 s0, s68, s16
	v_cndmask_b32_e32 v2, v5, v2, vcc
	v_mul_f32_e32 v149, 0xbfb8aa3b, v2
	v_mul_f32_e32 v2, 0x80000000, v140
	v_exp_f32_e32 v147, v2
	v_mul_f32_e32 v2, 0, v149
	v_exp_f32_e32 v148, v2
	v_mul_f32_e32 v2, -2.0, v140
	v_exp_f32_e32 v143, v2
	v_add_f32_e32 v2, v149, v149
	v_exp_f32_e32 v144, v2
	v_mul_f32_e32 v2, 0xc0400000, v140
	v_exp_f32_e32 v142, v2
	v_mul_f32_e32 v2, 0x40400000, v149
	v_exp_f32_e32 v141, v2
	v_or_b32_e32 v2, s5, v12
	v_add_u32_e32 v5, s3, v2
	s_addc_u32 s1, s69, 0
	v_and_b32_e32 v2, 48, v4
	v_lshl_add_u64 v[6:7], s[0:1], 0, v[2:3]
	v_mad_i64_i32 v[8:9], s[6:7], v5, s18, v[6:7]
	v_or_b32_e32 v5, 16, v5
	v_mad_i64_i32 v[6:7], s[6:7], v5, s18, v[6:7]
	global_load_dwordx4 v[90:93], v[8:9], off
	global_load_dwordx4 v[86:89], v[8:9], off offset:64
	global_load_dwordx4 v[82:85], v[8:9], off offset:128
	global_load_dwordx4 v[78:81], v[8:9], off offset:192
	global_load_dwordx4 v[58:61], v[6:7], off
	global_load_dwordx4 v[54:57], v[6:7], off offset:64
	global_load_dwordx4 v[46:49], v[6:7], off offset:128
	global_load_dwordx4 v[42:45], v[6:7], off offset:192
	v_add_u32_e32 v16, s3, v15
	v_mov_b64_e32 v[6:7], s[68:69]
	v_mad_i64_i32 v[8:9], s[6:7], v16, s18, v[6:7]
	v_lshlrev_b32_e32 v10, 4, v4
	v_lshl_add_u64 v[8:9], v[8:9], 0, s[16:17]
	v_and_b32_e32 v10, 0xf0, v10
	v_mov_b32_e32 v11, v3
	v_lshl_add_u64 v[8:9], v[8:9], 0, v[10:11]
	global_load_dwordx4 v[98:101], v[8:9], off offset:1024
	global_load_dwordx4 v[102:105], v[8:9], off offset:2048
	v_add_u32_e32 v8, 0x200, v4
	v_ashrrev_i32_e32 v8, 4, v8
	v_add_u32_e32 v9, s3, v8
	v_mad_i64_i32 v[6:7], s[6:7], v9, s18, v[6:7]
	v_lshl_add_u64 v[6:7], v[6:7], 0, s[16:17]
	v_lshl_add_u64 v[6:7], v[6:7], 0, v[10:11]
	global_load_dwordx4 v[106:109], v[6:7], off offset:1024
	global_load_dwordx4 v[110:113], v[6:7], off offset:2048
	v_exp_f32_e32 v146, v149
	v_lshlrev_b32_e32 v14, 3, v13
	v_lshlrev_b32_e32 v5, 3, v4
	v_lshlrev_b32_e32 v13, 2, v13
	v_bfe_u32 v4, v4, 2, 2
	s_add_i32 s6, s8, 0
	v_add_u32_e32 v6, 0, v10
	v_add_u32_e32 v7, 0, v2
	v_sub_u32_e32 v17, v12, v13
	v_or_b32_e32 v4, v14, v4
	v_and_b32_e32 v5, 24, v5
	s_movk_i32 s8, 0x110
	v_add_u32_e32 v150, s5, v17
	v_add_u32_e32 v17, s6, v14
	v_add_u32_e32 v2, s6, v2
	v_add_u32_e32 v5, 0, v5
	v_mad_u64_u32 v[136:137], s[6:7], v15, s8, v[6:7]
	v_mad_u64_u32 v[134:135], s[6:7], v8, s8, v[6:7]
	v_mul_u32_u24_e32 v6, 0x110, v12
	v_mul_u32_u24_e32 v8, 0x90, v12
	v_mul_u32_u24_e32 v4, 0x110, v4
	v_lshl_add_u64 v[138:139], s[0:1], 0, v[10:11]
	v_sub_u32_e32 v10, v13, v12
	v_subrev_u32_e32 v153, s5, v10
	v_add_u32_e32 v154, 64, v9
	v_add_u32_e32 v155, 64, v16
	s_movk_i32 s16, 0xffef
	v_add_u32_e32 v152, v7, v6
	v_add_u32_e32 v151, v17, v8
	v_add_u32_e32 v137, v2, v8
	v_add_u32_e32 v135, v5, v4
	v_mov_b32_e32 v156, v150
	v_mov_b32_e32 v2, v3
	v_mov_b32_e32 v4, v3
	v_mov_b32_e32 v5, v3
	v_mov_b32_e32 v6, v3
	v_mov_b32_e32 v7, v3
	v_mov_b32_e32 v8, v3
	v_mov_b32_e32 v9, v3
	v_mov_b32_e32 v10, v3
	v_mov_b32_e32 v12, v3
	v_mov_b32_e32 v13, v3
	v_mov_b32_e32 v14, v3
	v_mov_b32_e32 v15, v3
	v_mov_b32_e32 v16, v3
	v_mov_b32_e32 v17, v3
	v_mov_b32_e32 v18, v3
	v_mov_b32_e32 v19, v3
	v_mov_b32_e32 v20, v3
	v_readlane_b32 s30, v242, 14
	v_readlane_b32 s31, v242, 15

.Lh4b_main:
	v_lshlrev_b32_e32 v1, 4, v215
	v_add_u32_e32 v2, 0x2000, v1
	v_ashrrev_i32_e32 v3, 31, v2
	v_lshrrev_b32_e32 v3, 22, v3
	v_add_u32_e32 v3, v2, v3
	v_ashrrev_i32_e32 v10, 10, v3
	v_mul_i32_i24_e32 v3, 0x400, v10
	v_sub_u32_e32 v2, v2, v3
	v_lshrrev_b32_e32 v3, 4, v2
	v_bitop3_b32 v2, v3, v2, 32 bitop3:0x6c
	v_ashrrev_i32_e32 v3, 31, v2
	v_lshrrev_b32_e32 v3, 26, v3
	v_add_u32_e32 v3, v2, v3
	v_lshlrev_b32_e32 v4, 3, v10
	v_ashrrev_i32_e32 v11, 6, v3
	v_and_b32_e32 v4, -16, v4
	v_add_u32_e32 v4, v11, v4
	v_and_b32_e32 v5, 3, v11
	s_mov_b32 s0, 0x1fffe0
	v_lshrrev_b32_e32 v6, 2, v4
	v_lshlrev_b32_e32 v7, 1, v4
	v_and_b32_e32 v3, 0xc0, v3
	v_and_or_b32 v5, v4, s0, v5
	v_and_b32_e32 v6, 4, v6
	v_and_b32_e32 v7, 24, v7
	v_sub_u32_e32 v2, v2, v3
	v_mov_b32_e32 v3, 1
	v_or3_b32 v5, v5, v6, v7
	v_lshlrev_b32_e32 v6, 5, v10
	v_ashrrev_i16_sdwa v2, v3, sext(v2) dst_sel:DWORD dst_unused:UNUSED_PAD src0_sel:DWORD src1_sel:BYTE_0
	v_and_b32_e32 v6, 32, v6
	v_bfe_i32 v12, v2, 0, 16
	v_add_lshl_u32 v2, v6, v12, 1
	v_lshl_add_u32 v130, v5, 11, v2
	v_lshl_add_u32 v132, v4, 11, v2
	v_bfe_i32 v2, v215, 27, 1
	v_lshrrev_b32_e32 v2, 22, v2
	v_add_u32_e32 v2, v1, v2
	v_and_b32_e32 v2, 0xfffffc00, v2
	v_sub_u32_e32 v1, v1, v2
	v_lshrrev_b32_e32 v2, 4, v1
	v_ashrrev_i32_e32 v4, 31, v215
	v_bitop3_b32 v1, v2, v1, 32 bitop3:0x6c
	v_lshrrev_b32_e32 v4, 26, v4
	v_ashrrev_i32_e32 v2, 31, v1
	v_add_u32_e32 v4, v215, v4
	v_lshrrev_b32_e32 v2, 26, v2
	v_ashrrev_i32_e32 v14, 6, v4
	v_add_u32_e32 v2, v1, v2
	v_lshlrev_b32_e32 v4, 3, v14
	v_ashrrev_i32_e32 v13, 6, v2
	v_and_b32_e32 v4, -16, v4
	v_add_u32_e32 v4, v13, v4
	v_and_b32_e32 v5, 3, v13
	s_ashr_i32 s62, s38, 31
	v_and_or_b32 v5, v4, s0, v5
	s_lshr_b32 s0, s62, 29
	s_add_i32 s0, s38, s0
	s_ashr_i32 s34, s3, 6
	s_ashr_i32 s1, s0, 3
	s_and_b32 s0, s0, -8
	s_ashr_i32 s4, s3, 8
	s_lshl_b32 s37, s34, 10
	s_sub_i32 s0, s38, s0
	s_cmp_lt_i32 s0, 0
	s_cselect_b32 s5, 25, 24
	s_mul_i32 s0, s0, s5
	s_add_i32 s0, s0, s1
	s_mul_hi_i32 s1, s0, 0x2aaaaaab
	s_lshr_b32 s5, s1, 31
	s_ashr_i32 s1, s1, 2
	s_add_i32 s1, s1, s5
	s_mul_i32 s5, s1, 6
	s_mul_i32 s1, s1, 24
	s_sub_i32 s0, s0, s1
	s_bfe_i32 s1, s0, 0x80000
	s_mul_i32 s1, s1, 43
	s_bfe_u32 s6, s1, 0x1000f
	s_bfe_u32 s1, s1, 0x80008
	s_add_i32 s6, s1, s6
	s_mul_i32 s1, s6, 6
	s_sub_i32 s0, s0, s1
	s_sext_i32_i8 s0, s0
	v_lshrrev_b32_e32 v6, 2, v4
	v_lshlrev_b32_e32 v7, 1, v4
	v_and_b32_e32 v2, 0xc0, v2
	s_add_i32 s86, s5, s0
	v_and_b32_e32 v6, 4, v6
	v_and_b32_e32 v7, 24, v7
	v_sub_u32_e32 v1, v1, v2
	s_ashr_i32 s87, s86, 31
	s_bfe_i64 s[8:9], s[6:7], 0x80000
	v_or3_b32 v5, v5, v6, v7
	v_lshlrev_b32_e32 v6, 5, v14
	v_ashrrev_i16_sdwa v1, v3, sext(v1) dst_sel:DWORD dst_unused:UNUSED_PAD src0_sel:DWORD src1_sel:BYTE_0
	s_lshl_b64 s[0:1], s[86:87], 19
	s_lshl_b64 s[8:9], s[8:9], 19
	v_and_b32_e32 v6, 32, v6
	v_bfe_i32 v15, v1, 0, 16
	s_add_u32 s26, s70, s8
	v_add_lshl_u32 v1, v6, v15, 1
	s_addc_u32 s27, s71, s9
	s_add_i32 s63, s37, 0
	v_lshl_add_u32 v134, v5, 11, v1
	s_add_i32 m0, s63, 0x10000
	v_lshl_add_u32 v136, v4, 11, v1
	s_getpc_b64 s[100:101]
	v_lshlrev_b32_e32 v243, 7, v0
	v_min_u32_e32 v243, 0x1380, v243
	global_load_dword v243, v243, s[100:101]
	v_readfirstlane_b32 s98, v0
	s_cmp_gt_u32 s98, 63
	s_cbranch_scc1 .Lh4a_done
	s_getreg_b32 s98, hwreg(HW_REG_XCC_ID, 0, 4)
	s_lshl_b32 s98, s98, 8
	v_mov_b32_e32 v232, s98
	v_add_u32_e32 v232, 0x6400, v232
	s_mov_b32 s98, 0

.Lh5b_main:
	v_lshlrev_b32_e32 v1, 4, v12
	v_add_u32_e32 v2, 0x2000, v1
	v_ashrrev_i32_e32 v3, 31, v2
	v_lshrrev_b32_e32 v3, 22, v3
	v_add_u32_e32 v3, v2, v3
	v_ashrrev_i32_e32 v10, 10, v3
	v_mul_i32_i24_e32 v3, 0x400, v10
	v_sub_u32_e32 v2, v2, v3
	v_lshrrev_b32_e32 v3, 4, v2
	v_bitop3_b32 v2, v3, v2, 32 bitop3:0x6c
	v_ashrrev_i32_e32 v3, 31, v2
	v_lshrrev_b32_e32 v3, 26, v3
	v_add_u32_e32 v3, v2, v3
	v_lshlrev_b32_e32 v4, 3, v10
	v_ashrrev_i32_e32 v11, 6, v3
	v_and_b32_e32 v4, -16, v4
	v_add_u32_e32 v4, v11, v4
	v_and_b32_e32 v5, 3, v11
	s_mov_b32 s0, 0x1fffe0
	v_lshrrev_b32_e32 v6, 2, v4
	v_lshlrev_b32_e32 v7, 1, v4
	v_and_b32_e32 v3, 0xc0, v3
	v_and_or_b32 v5, v4, s0, v5
	v_and_b32_e32 v6, 4, v6
	v_and_b32_e32 v7, 24, v7
	v_sub_u32_e32 v2, v2, v3
	v_mov_b32_e32 v3, 1
	v_or3_b32 v5, v5, v6, v7
	v_lshlrev_b32_e32 v6, 5, v10
	v_ashrrev_i16_sdwa v2, v3, sext(v2) dst_sel:DWORD dst_unused:UNUSED_PAD src0_sel:DWORD src1_sel:BYTE_0
	v_and_b32_e32 v6, 32, v6
	v_bfe_i32 v13, v2, 0, 16
	v_add_lshl_u32 v2, v6, v13, 1
	v_lshl_add_u32 v146, v5, 11, v2
	v_lshl_add_u32 v148, v4, 11, v2
	v_bfe_i32 v2, v12, 27, 1
	v_lshrrev_b32_e32 v2, 22, v2
	v_add_u32_e32 v2, v1, v2
	v_and_b32_e32 v2, 0xfffffc00, v2
	v_sub_u32_e32 v1, v1, v2
	v_lshrrev_b32_e32 v2, 4, v1
	v_ashrrev_i32_e32 v4, 31, v12
	v_bitop3_b32 v1, v2, v1, 32 bitop3:0x6c
	v_lshrrev_b32_e32 v4, 26, v4
	v_ashrrev_i32_e32 v2, 31, v1
	v_add_u32_e32 v4, v12, v4
	v_lshrrev_b32_e32 v2, 26, v2
	v_ashrrev_i32_e32 v15, 6, v4
	v_add_u32_e32 v2, v1, v2
	v_lshlrev_b32_e32 v4, 3, v15
	v_ashrrev_i32_e32 v14, 6, v2
	v_and_b32_e32 v4, -16, v4
	v_add_u32_e32 v4, v14, v4
	v_and_b32_e32 v5, 3, v14
	v_and_or_b32 v5, v4, s0, v5
	s_ashr_i32 s0, s38, 31
	s_lshr_b32 s1, s0, 29
	s_add_i32 s1, s38, s1
	s_ashr_i32 s7, s4, 6
	s_ashr_i32 s6, s1, 3
	s_and_b32 s1, s1, -8
	s_ashr_i32 s5, s4, 8
	s_lshl_b32 s3, s7, 10
	s_sub_i32 s14, s38, s1
	s_cmp_lt_i32 s14, 0
	s_movk_i32 s1, 0x61
	s_cselect_b32 s15, s1, 0x60
	s_mul_i32 s14, s14, s15
	s_add_i32 s14, s14, s6
	s_mul_hi_i32 s6, s14, 0x2aaaaaab
	s_lshr_b32 s15, s6, 31
	s_ashr_i32 s6, s6, 4
	s_add_i32 s6, s6, s15
	s_mul_i32 s15, s6, 6
	s_mulk_i32 s6, 0x60
	s_sub_i32 s14, s14, s6
	s_bfe_i32 s6, s14, 0x80000
	s_mul_i32 s6, s6, 43
	s_bfe_u32 s16, s6, 0x1000f
	s_bfe_u32 s6, s6, 0x80008
	s_add_i32 s6, s6, s16
	s_mul_i32 s16, s6, 6
	s_sub_i32 s14, s14, s16
	s_sext_i32_i8 s14, s14
	v_lshrrev_b32_e32 v6, 2, v4
	v_lshlrev_b32_e32 v7, 1, v4
	v_and_b32_e32 v2, 0xc0, v2
	s_add_i32 s40, s15, s14
	v_and_b32_e32 v6, 4, v6
	v_and_b32_e32 v7, 24, v7
	v_sub_u32_e32 v1, v1, v2
	s_ashr_i32 s41, s40, 31
	s_bfe_i64 s[16:17], s[6:7], 0x80000
	v_or3_b32 v5, v5, v6, v7
	v_lshlrev_b32_e32 v6, 5, v15
	v_ashrrev_i16_sdwa v1, v3, sext(v1) dst_sel:DWORD dst_unused:UNUSED_PAD src0_sel:DWORD src1_sel:BYTE_0
	s_lshl_b64 s[14:15], s[40:41], 19
	s_lshl_b64 s[16:17], s[16:17], 19
	v_and_b32_e32 v6, 32, v6
	v_bfe_i32 v16, v1, 0, 16
	s_add_u32 s56, s88, s16
	v_add_lshl_u32 v1, v6, v16, 1
	s_addc_u32 s57, s89, s17
	s_add_i32 s41, s3, 0
	v_lshl_add_u32 v150, v5, 11, v1
	s_add_i32 m0, s41, 0x10000
	v_lshl_add_u32 v152, v4, 11, v1
	s_getpc_b64 s[100:101]
	v_lshlrev_b32_e32 v243, 7, v0
	v_min_u32_e32 v243, 0x1b80, v243
	global_load_dword v243, v243, s[100:101]
	v_readfirstlane_b32 s98, v0
	s_cmp_gt_u32 s98, 63
	s_cbranch_scc1 .Lh5a_done
	s_getreg_b32 s98, hwreg(HW_REG_XCC_ID, 0, 4)
	s_lshl_b32 s98, s98, 8
	v_mov_b32_e32 v226, s98
	v_add_u32_e32 v226, 0x6400, v226
	s_mov_b32 s98, 0

.LBB0_640:
	s_or_b64 exec, exec, s[6:7]
	v_readlane_b32 s0, v242, 38
	v_readlane_b32 s1, v242, 39
	s_waitcnt lgkmcnt(0)
	s_barrier
	s_and_b64 vcc, exec, s[0:1]
	v_readfirstlane_b32 s34, v0
	s_getpc_b64 s[100:101]
	v_lshlrev_b32_e32 v243, 7, v0
	v_min_u32_e32 v243, 0x1180, v243
	global_load_dword v243, v243, s[100:101]
	v_lshlrev_b32_e32 v1, 4, v0
	v_add_u32_e32 v2, 0x2000, v1
	v_ashrrev_i32_e32 v3, 31, v2
	v_lshrrev_b32_e32 v3, 22, v3
	v_add_u32_e32 v3, v2, v3
	v_ashrrev_i32_e32 v10, 10, v3
	v_mul_i32_i24_e32 v3, 0x400, v10
	v_sub_u32_e32 v2, v2, v3
	v_lshrrev_b32_e32 v3, 4, v2
	v_bitop3_b32 v2, v3, v2, 32 bitop3:0x6c
	v_ashrrev_i32_e32 v3, 31, v2
	v_lshrrev_b32_e32 v3, 26, v3
	v_add_u32_e32 v3, v2, v3
	v_lshlrev_b32_e32 v4, 3, v10
	v_ashrrev_i32_e32 v11, 6, v3
	v_and_b32_e32 v4, -16, v4
	v_add_u32_e32 v4, v11, v4
	v_and_b32_e32 v5, 3, v11
	s_mov_b32 s0, 0x7ffe0
	v_lshrrev_b32_e32 v6, 2, v4
	v_lshlrev_b32_e32 v7, 1, v4
	v_and_b32_e32 v3, 0xc0, v3
	v_and_or_b32 v5, v4, s0, v5
	v_and_b32_e32 v6, 4, v6
	v_and_b32_e32 v7, 24, v7
	v_sub_u32_e32 v2, v2, v3
	v_mov_b32_e32 v3, 1
	v_or3_b32 v5, v5, v6, v7
	v_lshlrev_b32_e32 v6, 5, v10
	v_ashrrev_i16_sdwa v2, v3, sext(v2) dst_sel:DWORD dst_unused:UNUSED_PAD src0_sel:DWORD src1_sel:BYTE_0
	v_and_b32_e32 v6, 32, v6
	v_bfe_i32 v12, v2, 0, 16
	v_add_lshl_u32 v2, v6, v12, 1
	v_lshl_add_u32 v122, v5, 13, v2
	v_lshl_add_u32 v124, v4, 13, v2
	v_add_u32_e32 v124, 0xfffe0000, v124
	v_bfe_i32 v2, v0, 27, 1
	v_lshrrev_b32_e32 v2, 22, v2
	v_add_u32_e32 v2, v1, v2
	v_and_b32_e32 v2, 0xfffffc00, v2
	v_sub_u32_e32 v1, v1, v2
	v_lshrrev_b32_e32 v2, 4, v1
	v_ashrrev_i32_e32 v4, 31, v0
	v_bitop3_b32 v1, v2, v1, 32 bitop3:0x6c
	v_lshrrev_b32_e32 v4, 26, v4
	v_ashrrev_i32_e32 v2, 31, v1
	v_add_u32_e32 v4, v0, v4
	v_lshrrev_b32_e32 v2, 26, v2
	v_ashrrev_i32_e32 v14, 6, v4
	v_add_u32_e32 v2, v1, v2
	v_lshlrev_b32_e32 v4, 3, v14
	v_ashrrev_i32_e32 v13, 6, v2
	v_and_b32_e32 v4, -16, v4
	v_add_u32_e32 v4, v13, v4
	v_and_b32_e32 v5, 3, v13
	s_ashr_i32 s36, s38, 31
	v_and_or_b32 v5, v4, s0, v5
	s_lshr_b32 s0, s36, 29
	s_add_i32 s0, s38, s0
	s_ashr_i32 s3, s34, 6
	s_ashr_i32 s1, s0, 3
	s_and_b32 s0, s0, -8
	s_ashr_i32 s11, s34, 8
	s_lshl_b32 s35, s3, 10
	s_sub_i32 s0, s38, s0
	s_cmp_lt_i32 s0, 0
	s_cselect_b32 s4, 25, 24
	s_mul_i32 s0, s0, s4
	s_add_i32 s0, s0, s1
	s_mul_hi_i32 s1, s0, 0x2aaaaaab
	s_lshr_b32 s4, s1, 31
	s_ashr_i32 s1, s1, 2
	s_add_i32 s1, s1, s4
	s_mul_i32 s4, s1, 6
	s_mul_i32 s1, s1, 24
	s_sub_i32 s1, s0, s1
	s_mul_i32 s0, s1, 43
	s_bfe_u32 s5, s0, 0x1000f
	s_bfe_u32 s0, s0, 0x80008
	s_add_i32 s0, s0, s5
	s_mul_i32 s5, s0, 6
	s_sub_i32 s1, s1, s5
	s_sext_i32_i8 s1, s1
	v_lshrrev_b32_e32 v6, 2, v4
	v_lshlrev_b32_e32 v7, 1, v4
	v_and_b32_e32 v2, 0xc0, v2
	s_add_i32 s6, s4, s1
	v_and_b32_e32 v6, 4, v6
	v_and_b32_e32 v7, 24, v7
	v_sub_u32_e32 v1, v1, v2
	s_lshr_b32 s1, s38, 3
	s_and_b32 s0, s1, 3
	s_lshr_b32 s1, s1, 2
	s_and_b32 s6, s38, 7
	s_lshl_b32 s6, s6, 3
	s_add_i32 s6, s6, s1
	s_ashr_i32 s7, s6, 31
	s_bfe_i64 s[14:15], s[0:1], 0x80000
	v_or3_b32 v5, v5, v6, v7
	v_lshlrev_b32_e32 v6, 5, v14
	v_ashrrev_i16_sdwa v1, v3, sext(v1) dst_sel:DWORD dst_unused:UNUSED_PAD src0_sel:DWORD src1_sel:BYTE_0
	s_mul_i32 s4, s6, 0x180000
	s_mov_b32 s5, 0
	s_lshl_b64 s[14:15], s[14:15], 21
	v_and_b32_e32 v6, 32, v6
	v_bfe_i32 v15, v1, 0, 16
	s_add_u32 s26, s86, s14
	v_add_lshl_u32 v1, v6, v15, 1
	s_addc_u32 s27, s87, s15
	s_add_i32 s37, s35, 0
	v_lshl_add_u32 v134, v5, 13, v1
	s_add_i32 m0, s37, 0x10000
	v_lshl_add_u32 v136, v4, 13, v1
	global_load_lds_dwordx4 v134, s[26:27]
	s_add_i32 m0, s37, 0x12000
	s_add_u32 s14, s26, 0x100000
	global_load_lds_dwordx4 v122, s[26:27]
	s_addc_u32 s15, s27, 0
	s_add_i32 m0, s37, 0x14000
	v_mov_b32_e32 v135, 0
	global_load_lds_dwordx4 v134, s[14:15]
	s_add_i32 m0, s37, 0x16000
	v_mov_b32_e32 v123, v135
	global_load_lds_dwordx4 v122, s[14:15]
	s_add_u32 s14, s68, s4
	s_addc_u32 s15, s69, s5
	s_add_i32 s41, s37, 0x2000
	s_mov_b32 m0, s37
	s_add_u32 s4, s14, 0xc0000
	global_load_lds_dwordx4 v136, s[14:15]
	s_mov_b32 m0, s41
	s_addc_u32 s5, s15, 0
	s_add_i32 s42, s37, 0x4000
	global_load_lds_dwordx4 v124, s[14:15]
	s_mov_b32 m0, s42
	s_add_i32 s43, s37, 0x6000
	global_load_lds_dwordx4 v136, s[4:5]
	s_mov_b32 m0, s43
	v_mov_b32_e32 v137, v135
	global_load_lds_dwordx4 v124, s[4:5]
	v_mov_b32_e32 v125, v135
	s_mov_b32 s44, 0
	v_lshl_add_u64 v[8:9], s[26:27], 0, v[134:135]
	v_lshl_add_u64 v[6:7], s[26:27], 0, v[122:123]
	v_lshl_add_u64 v[4:5], s[14:15], 0, v[136:137]
	s_cmp_lg_u32 s11, 1
	v_lshl_add_u64 v[2:3], s[14:15], 0, v[124:125]
	s_cbranch_scc1 .LBB0_643
	s_barrier
